# final sample-row pass: final_g blocks held in registers, stores no longer serialized behind final_g reloads
# speedup vs baseline: 1.0074x; 1.0074x over previous
.LBB0_1221:
	s_or_b64 exec, exec, s[0:1]
	v_readlane_b32 s0, v252, 14
	v_readlane_b32 s1, v252, 15
	s_and_b64 vcc, exec, s[0:1]
	s_waitcnt lgkmcnt(0)
	s_barrier
	s_cbranch_vccz .LBB0_1225
	s_add_i32 s0, s17, 0x4000
	v_ashrrev_i32_e32 v0, 5, v232
	v_and_b32_e32 v8, -2, v0
	v_add_u32_e32 v6, s0, v8
	s_movk_i32 s0, 0x4400
	s_movk_i32 s8, 0x4000
	v_cmp_gt_i32_e32 vcc, s0, v6
	s_and_saveexec_b64 s[0:1], vcc
	s_cbranch_execz .LBB0_1225
	v_lshlrev_b32_e32 v0, 2, v232
	v_and_b32_e32 v12, 0xfc, v0
	v_mov_b32_e32 v1, 0
	v_lshlrev_b32_e32 v0, 2, v12
	v_lshl_add_u64 v[2:3], s[24:25], 0, v[0:1]
	v_and_b32_e32 v0, 64, v233
	v_add_u32_e32 v0, 64, v0
	v_xor_b32_e32 v4, 1, v233
	v_cmp_lt_i32_e32 vcc, v4, v0
	v_ashrrev_i32_e32 v7, 31, v6
	s_mov_b64 s[0:1], 0x1000
	v_cndmask_b32_e32 v4, v233, v4, vcc
	v_lshlrev_b32_e32 v26, 2, v4
	v_xor_b32_e32 v4, 2, v233
	v_cmp_lt_i32_e32 vcc, v4, v0
	v_or_b32_e32 v14, 0x100, v12
	v_or_b32_e32 v16, 0x200, v12
	v_cndmask_b32_e32 v4, v233, v4, vcc
	v_lshlrev_b32_e32 v27, 2, v4
	v_xor_b32_e32 v4, 4, v233
	v_cmp_lt_i32_e32 vcc, v4, v0
	v_or_b32_e32 v18, 0x300, v12
	v_add_u32_e32 v8, s17, v8
	v_cndmask_b32_e32 v4, v233, v4, vcc
	v_lshlrev_b32_e32 v28, 2, v4
	v_xor_b32_e32 v4, 8, v233
	v_cmp_lt_i32_e32 vcc, v4, v0
	s_mov_b64 s[2:3], 0
	s_mov_b64 s[4:5], 0x400000
	v_cndmask_b32_e32 v4, v233, v4, vcc
	v_lshlrev_b32_e32 v29, 2, v4
	v_xor_b32_e32 v4, 16, v233
	v_cmp_lt_i32_e32 vcc, v4, v0
	s_mov_b32 s9, 0xc000
	v_mov_b64_e32 v[10:11], s[84:85]
	v_cndmask_b32_e32 v4, v233, v4, vcc
	v_lshlrev_b32_e32 v30, 2, v4
	v_xor_b32_e32 v4, 32, v233
	v_cmp_lt_i32_e32 vcc, v4, v0
	s_mov_b64 s[6:7], 0x578b000
	v_mov_b32_e32 v13, v1
	v_cndmask_b32_e32 v0, v233, v4, vcc
	v_lshlrev_b32_e32 v31, 2, v0
	v_lshlrev_b64 v[4:5], 12, v[6:7]
	v_and_b32_e32 v0, 63, v232
	v_lshl_or_b32 v4, v0, 4, v4
	v_lshlrev_b64 v[6:7], 11, v[6:7]
	v_lshl_add_u64 v[4:5], s[26:27], 0, v[4:5]
	v_lshl_or_b32 v6, v0, 3, v6
	v_lshl_add_u64 v[4:5], v[4:5], 0, s[0:1]
	v_lshl_add_u64 v[6:7], s[84:85], 0, v[6:7]
	s_mov_b64 s[0:1], 0x8e38e00
	v_lshl_add_u64 v[6:7], v[6:7], 0, s[0:1]
	s_lshl_b64 s[0:1], s[20:21], 11
	v_lshlrev_b32_e32 v0, 2, v12
	v_lshlrev_b32_e32 v12, 2, v14
	v_lshlrev_b32_e32 v14, 2, v16
	v_mov_b32_e32 v15, v1
	v_lshlrev_b32_e32 v16, 2, v18
	v_mov_b32_e32 v17, v1
	v_mov_b32_e32 v32, 0x358637bd
	s_mov_b32 s10, 0x800000
	s_movk_i32 s11, 0x3fff
	s_movk_i32 s12, 0x43ff
	global_load_dwordx4 v[108:111], v[2:3], off offset:1024
	global_load_dwordx4 v[112:115], v[2:3], off offset:2048
	global_load_dwordx4 v[116:119], v[2:3], off offset:3072
.LBB0_1224:
	v_ashrrev_i32_e32 v9, 31, v8
	v_add_u32_e32 v33, 0x4000, v8
	v_lshrrev_b32_e32 v40, 3, v8
	v_lshlrev_b64 v[38:39], 12, v[8:9]
	v_ashrrev_i32_e32 v9, 11, v33
	v_add_u32_e32 v40, 8, v40
	v_cmp_gt_i32_e32 vcc, s8, v33
	v_lshl_add_u64 v[38:39], s[88:89], 0, v[38:39]
	v_lshl_add_u64 v[54:55], v[38:39], 0, s[4:5]
	v_cndmask_b32_e32 v40, v40, v9, vcc
	v_mad_i64_i32 v[40:41], s[14:15], v40, s9, v[10:11]
	v_lshl_add_u64 v[56:57], v[38:39], 0, v[0:1]
	v_lshl_add_u64 v[58:59], v[54:55], 0, v[0:1]
	v_lshl_add_u64 v[60:61], v[54:55], 0, v[12:13]
	v_lshl_add_u64 v[62:63], v[54:55], 0, v[14:15]
	global_load_dwordx2 v[86:87], v[6:7], off offset:-3584
	global_load_dwordx2 v[88:89], v[6:7], off offset:-3072
	global_load_dwordx2 v[90:91], v[6:7], off offset:-2560
	global_load_dwordx2 v[92:93], v[6:7], off offset:-2048
	global_load_dwordx2 v[18:19], v[6:7], off offset:-1536
	global_load_dwordx2 v[20:21], v[6:7], off offset:-1024
	global_load_dwordx2 v[22:23], v[6:7], off offset:-512
	global_load_dwordx2 v[24:25], v[6:7], off
	global_load_dwordx4 v[34:37], v[2:3], off
	v_lshl_add_u64 v[70:71], v[40:41], 0, s[6:7]
	global_load_dwordx4 v[38:41], v[56:57], off
	global_load_dwordx4 v[42:45], v[56:57], off offset:1024
	global_load_dwordx4 v[46:49], v[56:57], off offset:2048
	global_load_dwordx4 v[50:53], v[56:57], off offset:3072
	v_lshl_add_u64 v[66:67], v[54:55], 0, v[16:17]
	global_load_dwordx4 v[54:57], v[58:59], off
	v_lshl_add_u64 v[94:95], v[70:71], 0, v[0:1]
	global_load_dwordx4 v[62:65], v[62:63], off
	v_lshl_add_u64 v[96:97], v[70:71], 0, v[12:13]
	global_load_dwordx4 v[58:61], v[60:61], off
	v_lshl_add_u64 v[98:99], v[70:71], 0, v[14:15]
	global_load_dwordx4 v[66:69], v[66:67], off
	v_lshl_add_u64 v[100:101], v[70:71], 0, v[16:17]
	global_load_dwordx4 v[70:73], v[94:95], off
	global_load_dwordx4 v[74:77], v[96:97], off
	global_load_dwordx4 v[78:81], v[98:99], off
	global_load_dwordx4 v[82:85], v[100:101], off
	v_lshl_add_u64 v[6:7], v[6:7], 0, s[0:1]
	s_waitcnt vmcnt(20)
	v_lshlrev_b32_e32 v94, 16, v86
	v_and_b32_e32 v95, 0xffff0000, v86
	v_lshlrev_b32_e32 v86, 16, v87
	v_and_b32_e32 v87, 0xffff0000, v87
	s_waitcnt vmcnt(19)
	v_lshlrev_b32_e32 v96, 16, v88
	v_and_b32_e32 v97, 0xffff0000, v88
	v_lshlrev_b32_e32 v88, 16, v89
	v_and_b32_e32 v89, 0xffff0000, v89
	s_waitcnt vmcnt(18)
	v_lshlrev_b32_e32 v98, 16, v90
	v_and_b32_e32 v99, 0xffff0000, v90
	v_lshlrev_b32_e32 v90, 16, v91
	v_and_b32_e32 v91, 0xffff0000, v91
	s_waitcnt vmcnt(17)
	v_lshlrev_b32_e32 v100, 16, v92
	s_waitcnt vmcnt(7)
	v_pk_add_f32 v[40:41], v[40:41], v[56:57]
	v_pk_add_f32 v[38:39], v[38:39], v[54:55]
	v_and_b32_e32 v101, 0xffff0000, v92
	v_lshlrev_b32_e32 v92, 16, v93
	s_waitcnt vmcnt(5)
	v_pk_add_f32 v[44:45], v[44:45], v[60:61]
	v_pk_add_f32 v[42:43], v[42:43], v[58:59]
	s_waitcnt vmcnt(3)
	v_pk_add_f32 v[54:55], v[72:73], 1.0 op_sel_hi:[1,0]
	v_pk_add_f32 v[56:57], v[70:71], 1.0 op_sel_hi:[1,0]
	s_waitcnt vmcnt(2)
	v_pk_add_f32 v[58:59], v[76:77], 1.0 op_sel_hi:[1,0]
	v_pk_add_f32 v[60:61], v[74:75], 1.0 op_sel_hi:[1,0]
	v_pk_fma_f32 v[40:41], v[40:41], v[54:55], v[86:87]
	v_pk_fma_f32 v[38:39], v[38:39], v[56:57], v[94:95]
	v_pk_fma_f32 v[44:45], v[44:45], v[58:59], v[88:89]
	v_pk_fma_f32 v[42:43], v[42:43], v[60:61], v[96:97]
	v_and_b32_e32 v93, 0xffff0000, v93
	v_pk_add_f32 v[48:49], v[48:49], v[64:65]
	v_pk_add_f32 v[46:47], v[46:47], v[62:63]
	v_pk_add_f32 v[52:53], v[52:53], v[68:69]
	v_pk_add_f32 v[50:51], v[50:51], v[66:67]
	s_waitcnt vmcnt(1)
	v_pk_add_f32 v[62:63], v[80:81], 1.0 op_sel_hi:[1,0]
	v_pk_add_f32 v[64:65], v[78:79], 1.0 op_sel_hi:[1,0]
	s_waitcnt vmcnt(0)
	v_pk_add_f32 v[66:67], v[84:85], 1.0 op_sel_hi:[1,0]
	v_pk_add_f32 v[68:69], v[82:83], 1.0 op_sel_hi:[1,0]
	v_pk_mul_f32 v[54:55], v[40:41], v[40:41]
	v_pk_mul_f32 v[56:57], v[38:39], v[38:39]
	v_pk_mul_f32 v[58:59], v[44:45], v[44:45]
	v_pk_mul_f32 v[60:61], v[42:43], v[42:43]
	v_pk_fma_f32 v[48:49], v[48:49], v[62:63], v[90:91]
	v_pk_fma_f32 v[46:47], v[46:47], v[64:65], v[98:99]
	v_pk_fma_f32 v[52:53], v[52:53], v[66:67], v[92:93]
	v_pk_fma_f32 v[50:51], v[50:51], v[68:69], v[100:101]
	v_pk_mov_b32 v[66:67], v[56:57], v[54:55] op_sel:[1,0]
	v_mov_b32_e32 v57, v55
	v_pk_mov_b32 v[54:55], v[60:61], v[58:59] op_sel:[1,0]
	v_mov_b32_e32 v61, v59
	v_mul_f32_e32 v65, v50, v50
	v_mul_f32_e32 v62, v47, v47
	v_mul_f32_e32 v64, v49, v49
	v_pk_add_f32 v[56:57], v[66:67], v[56:57]
	v_pk_add_f32 v[54:55], v[54:55], v[60:61]
	v_mul_f32_e32 v68, v51, v51
	v_mul_f32_e32 v69, v52, v52
	v_mul_f32_e32 v70, v53, v53
	v_pk_fma_f32 v[58:59], v[46:47], v[46:47], v[62:63] op_sel_hi:[1,1,0]
	v_pk_fma_f32 v[62:63], v[48:49], v[48:49], v[64:65] op_sel_hi:[1,1,0]
	v_pk_add_f32 v[56:57], v[56:57], v[56:57] op_sel:[0,1] op_sel_hi:[1,0]
	v_pk_add_f32 v[54:55], v[54:55], v[54:55] op_sel:[0,1] op_sel_hi:[1,0]
	v_mov_b32_e32 v59, v69
	v_mov_b32_e32 v63, v70
	v_mov_b32_e32 v57, v65
	v_mov_b32_e32 v55, v68
	v_pk_add_f32 v[58:59], v[58:59], v[62:63]
	v_pk_add_f32 v[54:55], v[56:57], v[54:55]
	s_nop 0
	v_pk_add_f32 v[54:55], v[54:55], v[58:59]
	s_nop 0
	v_add_f32_e32 v54, v54, v55
	ds_bpermute_b32 v55, v26, v54
	s_waitcnt lgkmcnt(0)
	v_add_f32_e32 v54, v54, v55
	ds_bpermute_b32 v55, v27, v54
	s_waitcnt lgkmcnt(0)
	v_add_f32_e32 v54, v54, v55
	ds_bpermute_b32 v55, v28, v54
	s_waitcnt lgkmcnt(0)
	v_add_f32_e32 v54, v54, v55
	ds_bpermute_b32 v55, v29, v54
	s_waitcnt lgkmcnt(0)
	v_add_f32_e32 v54, v54, v55
	ds_bpermute_b32 v55, v30, v54
	s_waitcnt lgkmcnt(0)
	v_add_f32_e32 v54, v54, v55
	ds_bpermute_b32 v55, v31, v54
	s_waitcnt lgkmcnt(0)
	v_add_f32_e32 v54, v54, v55
	v_fmamk_f32 v54, v54, 0x3a800000, v32
	v_mul_f32_e32 v55, 0x4b800000, v54
	v_cmp_gt_f32_e32 vcc, s10, v54
	s_nop 1
	v_cndmask_b32_e32 v54, v54, v55, vcc
	v_rsq_f32_e32 v54, v54
	s_nop 0
	v_mul_f32_e32 v55, 0x45800000, v54
	v_cndmask_b32_e32 v54, v54, v55, vcc
	v_pk_mul_f32 v[38:39], v[38:39], v[54:55] op_sel_hi:[1,0]
	v_pk_mul_f32 v[40:41], v[40:41], v[54:55] op_sel_hi:[1,0]
	v_pk_mul_f32 v[34:35], v[34:35], v[38:39]
	v_pk_mul_f32 v[36:37], v[36:37], v[40:41]
	global_store_dwordx4 v[4:5], v[34:37], off offset:-4096
	v_pk_mul_f32 v[38:39], v[44:45], v[54:55] op_sel_hi:[1,0]
	v_pk_mul_f32 v[40:41], v[42:43], v[54:55] op_sel_hi:[1,0]
	v_cmp_gt_i32_e32 vcc, s11, v33
	v_pk_mul_f32 v[34:35], v[108:109], v[40:41]
	v_pk_mul_f32 v[36:37], v[110:111], v[38:39]
	global_store_dwordx4 v[4:5], v[34:37], off offset:-3072
	v_pk_mul_f32 v[38:39], v[48:49], v[54:55] op_sel_hi:[1,0]
	v_pk_mul_f32 v[40:41], v[46:47], v[54:55] op_sel_hi:[1,0]
	s_nop 0
	v_pk_mul_f32 v[36:37], v[114:115], v[38:39]
	v_pk_mul_f32 v[34:35], v[112:113], v[40:41]
	global_store_dwordx4 v[4:5], v[34:37], off offset:-2048
	v_add_u32_e32 v38, 1, v8
	v_lshrrev_b32_e32 v40, 3, v38
	v_ashrrev_i32_e32 v39, 31, v38
	v_add_u32_e32 v40, 8, v40
	v_lshlrev_b64 v[38:39], 12, v[38:39]
	v_cndmask_b32_e32 v9, v40, v9, vcc
	v_lshl_add_u64 v[38:39], s[88:89], 0, v[38:39]
	v_mad_i64_i32 v[42:43], s[14:15], v9, s9, v[10:11]
	v_lshl_add_u64 v[40:41], v[38:39], 0, s[4:5]
	v_lshl_add_u64 v[82:83], v[38:39], 0, v[0:1]
	v_lshl_add_u64 v[38:39], v[42:43], 0, s[6:7]
	v_lshl_add_u64 v[84:85], v[40:41], 0, v[0:1]
	v_lshl_add_u64 v[86:87], v[40:41], 0, v[12:13]
	v_lshl_add_u64 v[88:89], v[40:41], 0, v[14:15]
	v_lshl_add_u64 v[90:91], v[40:41], 0, v[16:17]
	v_lshl_add_u64 v[92:93], v[38:39], 0, v[0:1]
	v_lshl_add_u64 v[94:95], v[38:39], 0, v[12:13]
	v_lshl_add_u64 v[96:97], v[38:39], 0, v[14:15]
	v_lshl_add_u64 v[98:99], v[38:39], 0, v[16:17]
	v_pk_mul_f32 v[38:39], v[52:53], v[54:55] op_sel_hi:[1,0]
	v_pk_mul_f32 v[40:41], v[50:51], v[54:55] op_sel_hi:[1,0]
	v_add_u32_e32 v8, s20, v8
	v_pk_mul_f32 v[34:35], v[116:117], v[40:41]
	v_pk_mul_f32 v[36:37], v[118:119], v[38:39]
	global_store_dwordx4 v[4:5], v[34:37], off offset:-1024
	global_load_dwordx4 v[34:37], v[82:83], off
	s_nop 0
	global_load_dwordx4 v[38:41], v[84:85], off
	global_load_dwordx4 v[42:45], v[92:93], off
	global_load_dwordx4 v[46:49], v[82:83], off offset:1024
	global_load_dwordx4 v[50:53], v[86:87], off
	global_load_dwordx4 v[54:57], v[94:95], off
	global_load_dwordx4 v[58:61], v[82:83], off offset:2048
	global_load_dwordx4 v[62:65], v[88:89], off
	global_load_dwordx4 v[66:69], v[96:97], off
	global_load_dwordx4 v[70:73], v[82:83], off offset:3072
	global_load_dwordx4 v[74:77], v[90:91], off
	global_load_dwordx4 v[78:81], v[98:99], off
	v_lshlrev_b32_e32 v82, 16, v18
	v_and_b32_e32 v83, 0xffff0000, v18
	v_lshlrev_b32_e32 v84, 16, v19
	v_and_b32_e32 v85, 0xffff0000, v19
	v_lshlrev_b32_e32 v86, 16, v20
	v_and_b32_e32 v87, 0xffff0000, v20
	v_lshlrev_b32_e32 v88, 16, v21
	v_and_b32_e32 v89, 0xffff0000, v21
	global_load_dwordx4 v[18:21], v[2:3], off
	v_lshlrev_b32_e32 v90, 16, v22
	v_and_b32_e32 v91, 0xffff0000, v22
	v_lshlrev_b32_e32 v22, 16, v23
	v_and_b32_e32 v23, 0xffff0000, v23
	v_lshlrev_b32_e32 v92, 16, v24
	v_and_b32_e32 v93, 0xffff0000, v24
	v_lshlrev_b32_e32 v24, 16, v25
	v_and_b32_e32 v25, 0xffff0000, v25
	s_waitcnt vmcnt(11)
	v_pk_add_f32 v[36:37], v[36:37], v[40:41]
	v_pk_add_f32 v[34:35], v[34:35], v[38:39]
	s_waitcnt vmcnt(10)
	v_pk_add_f32 v[38:39], v[44:45], 1.0 op_sel_hi:[1,0]
	v_pk_add_f32 v[40:41], v[42:43], 1.0 op_sel_hi:[1,0]
	s_waitcnt vmcnt(8)
	v_pk_add_f32 v[42:43], v[48:49], v[52:53]
	v_pk_add_f32 v[44:45], v[46:47], v[50:51]
	s_waitcnt vmcnt(7)
	v_pk_add_f32 v[46:47], v[56:57], 1.0 op_sel_hi:[1,0]
	v_pk_add_f32 v[48:49], v[54:55], 1.0 op_sel_hi:[1,0]
	s_waitcnt vmcnt(5)
	v_pk_add_f32 v[50:51], v[60:61], v[64:65]
	v_pk_add_f32 v[52:53], v[58:59], v[62:63]
	s_waitcnt vmcnt(4)
	v_pk_add_f32 v[54:55], v[68:69], 1.0 op_sel_hi:[1,0]
	v_pk_add_f32 v[56:57], v[66:67], 1.0 op_sel_hi:[1,0]
	v_pk_fma_f32 v[36:37], v[36:37], v[38:39], v[84:85]
	v_pk_fma_f32 v[34:35], v[34:35], v[40:41], v[82:83]
	v_pk_fma_f32 v[38:39], v[42:43], v[46:47], v[88:89]
	v_pk_fma_f32 v[40:41], v[44:45], v[48:49], v[86:87]
	s_waitcnt vmcnt(2)
	v_pk_add_f32 v[58:59], v[72:73], v[76:77]
	s_waitcnt vmcnt(1)
	v_pk_add_f32 v[62:63], v[80:81], 1.0 op_sel_hi:[1,0]
	v_pk_fma_f32 v[22:23], v[50:51], v[54:55], v[22:23]
	v_pk_fma_f32 v[42:43], v[52:53], v[56:57], v[90:91]
	v_pk_mul_f32 v[46:47], v[36:37], v[36:37]
	v_pk_mul_f32 v[48:49], v[34:35], v[34:35]
	v_pk_mul_f32 v[50:51], v[38:39], v[38:39]
	v_pk_mul_f32 v[52:53], v[40:41], v[40:41]
	v_pk_add_f32 v[60:61], v[70:71], v[74:75]
	v_pk_add_f32 v[64:65], v[78:79], 1.0 op_sel_hi:[1,0]
	v_pk_fma_f32 v[24:25], v[58:59], v[62:63], v[24:25]
	v_pk_mov_b32 v[58:59], v[48:49], v[46:47] op_sel:[1,0]
	v_mov_b32_e32 v49, v47
	v_pk_mov_b32 v[46:47], v[52:53], v[50:51] op_sel:[1,0]
	v_mov_b32_e32 v53, v51
	v_pk_fma_f32 v[44:45], v[60:61], v[64:65], v[92:93]
	v_mul_f32_e32 v57, v24, v24
	v_mul_f32_e32 v54, v43, v43
	v_mul_f32_e32 v56, v23, v23
	v_pk_add_f32 v[48:49], v[58:59], v[48:49]
	v_pk_add_f32 v[46:47], v[46:47], v[52:53]
	v_mul_f32_e32 v9, v44, v44
	v_mul_f32_e32 v33, v45, v45
	v_mul_f32_e32 v60, v25, v25
	v_pk_fma_f32 v[50:51], v[42:43], v[42:43], v[54:55] op_sel_hi:[1,1,0]
	v_pk_fma_f32 v[54:55], v[22:23], v[22:23], v[56:57] op_sel_hi:[1,1,0]
	v_pk_add_f32 v[48:49], v[48:49], v[48:49] op_sel:[0,1] op_sel_hi:[1,0]
	v_pk_add_f32 v[46:47], v[46:47], v[46:47] op_sel:[0,1] op_sel_hi:[1,0]
	v_mov_b32_e32 v51, v57
	v_mov_b32_e32 v55, v60
	v_mov_b32_e32 v49, v9
	v_mov_b32_e32 v47, v33
	v_pk_add_f32 v[50:51], v[50:51], v[54:55]
	v_pk_add_f32 v[46:47], v[48:49], v[46:47]
	s_nop 0
	v_pk_add_f32 v[46:47], v[46:47], v[50:51]
	s_nop 0
	v_add_f32_e32 v9, v46, v47
	ds_bpermute_b32 v33, v26, v9
	s_waitcnt lgkmcnt(0)
	v_add_f32_e32 v9, v9, v33
	ds_bpermute_b32 v33, v27, v9
	s_waitcnt lgkmcnt(0)
	v_add_f32_e32 v9, v9, v33
	ds_bpermute_b32 v33, v28, v9
	s_waitcnt lgkmcnt(0)
	v_add_f32_e32 v9, v9, v33
	ds_bpermute_b32 v33, v29, v9
	s_waitcnt lgkmcnt(0)
	v_add_f32_e32 v9, v9, v33
	ds_bpermute_b32 v33, v30, v9
	s_waitcnt lgkmcnt(0)
	v_add_f32_e32 v9, v9, v33
	ds_bpermute_b32 v33, v31, v9
	s_waitcnt lgkmcnt(0)
	v_add_f32_e32 v9, v9, v33
	v_fmamk_f32 v9, v9, 0x3a800000, v32
	v_mul_f32_e32 v33, 0x4b800000, v9
	v_cmp_gt_f32_e32 vcc, s10, v9
	s_nop 1
	v_cndmask_b32_e32 v9, v9, v33, vcc
	v_rsq_f32_e32 v9, v9
	s_nop 0
	v_mul_f32_e32 v33, 0x45800000, v9
	v_cndmask_b32_e32 v46, v9, v33, vcc
	v_pk_mul_f32 v[34:35], v[34:35], v[46:47] op_sel_hi:[1,0]
	v_pk_mul_f32 v[36:37], v[36:37], v[46:47] op_sel_hi:[1,0]
	s_waitcnt vmcnt(0)
	v_pk_mul_f32 v[18:19], v[18:19], v[34:35]
	v_pk_mul_f32 v[20:21], v[20:21], v[36:37]
	global_store_dwordx4 v[4:5], v[18:21], off
	v_pk_mul_f32 v[34:35], v[38:39], v[46:47] op_sel_hi:[1,0]
	v_pk_mul_f32 v[36:37], v[40:41], v[46:47] op_sel_hi:[1,0]
	v_pk_mul_f32 v[22:23], v[22:23], v[46:47] op_sel_hi:[1,0]
	v_add_u32_e32 v9, 0x4000, v8
	v_cmp_lt_i32_e32 vcc, s12, v9
	s_or_b64 s[2:3], vcc, s[2:3]
	v_pk_mul_f32 v[18:19], v[108:109], v[36:37]
	v_pk_mul_f32 v[20:21], v[110:111], v[34:35]
	global_store_dwordx4 v[4:5], v[18:21], off offset:1024
	v_pk_mul_f32 v[34:35], v[42:43], v[46:47] op_sel_hi:[1,0]
	s_nop 1
	v_pk_mul_f32 v[20:21], v[114:115], v[22:23]
	v_pk_mul_f32 v[18:19], v[112:113], v[34:35]
	global_store_dwordx4 v[4:5], v[18:21], off offset:2048
	v_pk_mul_f32 v[22:23], v[24:25], v[46:47] op_sel_hi:[1,0]
	v_pk_mul_f32 v[24:25], v[44:45], v[46:47] op_sel_hi:[1,0]
	s_nop 0
	v_pk_mul_f32 v[20:21], v[118:119], v[22:23]
	v_pk_mul_f32 v[18:19], v[116:117], v[24:25]
	global_store_dwordx4 v[4:5], v[18:21], off offset:3072
	v_lshl_add_u64 v[4:5], v[4:5], 0, s[18:19]
	s_andn2_b64 exec, exec, s[2:3]
	s_cbranch_execnz .LBB0_1224
